# CONV loop rewritten: invariant bias/tap quads loaded once; the four row loads of an item issued together with counted waits (one round trip per item instead of eight)
# speedup vs baseline: 1.0113x; 1.0113x over previous
.LBB0_1235:
	v_ashrrev_i32_e32 v0, 8, v12
	v_cmp_gt_i32_e32 vcc, s92, v0
	v_mov_b32_e32 v2, 0x7fffff00
	v_mov_b32_e32 v3, 0xffffe000
	v_cndmask_b32_e32 v2, v2, v3, vcc
	v_cndmask_b32_e32 v3, v227, v238, vcc
	v_cndmask_b32_e32 v13, v155, v253, vcc
	v_and_b32_e32 v28, v3, v0
	v_and_b32_e32 v25, v2, v0
	v_lshlrev_b32_e32 v1, 2, v12
	v_and_b32_e32 v1, 0x3fc, v1
	v_lshlrev_b32_e32 v2, 1, v1
	v_mov_b32_e32 v3, v153
	v_lshl_add_u64 v[6:7], s[8:9], 0, v[2:3]
	v_add_u32_e32 v30, -2, v28
	v_cmp_lt_u32_e32 vcc, 1, v28
	v_cmp_lt_u32_e64 s[0:1], v30, v13
	s_and_b64 vcc, vcc, s[0:1]
	v_cndmask_b32_e32 v30, v28, v30, vcc
	v_cndmask_b32_e64 v40, 0, 1.0, vcc
	v_add_u32_e32 v30, v30, v25
	v_ashrrev_i32_e32 v31, 31, v30
	v_lshlrev_b64 v[30:31], 11, v[30:31]
	v_lshl_add_u64 v[30:31], v[6:7], 0, v[30:31]
	global_load_dwordx2 v[48:49], v[30:31], off
	v_add_u32_e32 v32, -1, v28
	v_cmp_lt_u32_e32 vcc, v32, v13
	s_nop 1
	v_cndmask_b32_e64 v42, 0, 1.0, vcc
	v_add_u32_e32 v18, v25, v28
	s_nop 1
	v_subbrev_co_u32_e64 v32, s[0:1], 0, v18, vcc
	v_ashrrev_i32_e32 v33, 31, v32
	v_lshlrev_b64 v[32:33], 11, v[32:33]
	v_lshl_add_u64 v[32:33], v[6:7], 0, v[32:33]
	global_load_dwordx2 v[50:51], v[32:33], off
	v_cmp_lt_u32_e32 vcc, v28, v13
	s_nop 1
	v_cndmask_b32_e64 v44, 0, 1.0, vcc
	v_ashrrev_i32_e32 v19, 31, v18
	v_lshlrev_b64 v[34:35], 11, v[18:19]
	v_lshl_add_u64 v[34:35], v[6:7], 0, v[34:35]
	global_load_dwordx2 v[52:53], v[34:35], off
	v_add_u32_e32 v36, 1, v28
	v_cmp_lt_u32_e32 vcc, v36, v13
	s_nop 1
	v_cndmask_b32_e32 v36, v28, v36, vcc
	v_cndmask_b32_e64 v46, 0, 1.0, vcc
	v_add_u32_e32 v36, v36, v25
	v_ashrrev_i32_e32 v37, 31, v36
	v_lshlrev_b64 v[36:37], 11, v[36:37]
	v_lshl_add_u64 v[36:37], v[6:7], 0, v[36:37]
	global_load_dwordx2 v[54:55], v[36:37], off
	v_ashrrev_i32_e32 v1, 31, v0
	v_lshlrev_b64 v[0:1], 11, v[0:1]
	v_lshl_add_u64 v[0:1], s[10:11], 0, v[0:1]
	v_lshl_add_u64 v[0:1], v[0:1], 0, v[2:3]
	v_add_u32_e32 v12, s24, v12
	v_cmp_lt_i32_e32 vcc, s46, v12
	s_nop 1
	s_or_b64 s[12:13], vcc, s[12:13]
	s_waitcnt vmcnt(3)
	v_lshlrev_b32_e32 v20, 16, v48
	v_and_b32_e32 v21, 0xffff0000, v48
	v_lshlrev_b32_e32 v22, 16, v49
	v_and_b32_e32 v23, 0xffff0000, v49
	v_pk_mul_f32 v[14:15], v[68:69], v[20:21]
	v_pk_mul_f32 v[16:17], v[70:71], v[22:23]
	v_pk_fma_f32 v[14:15], v[14:15], v[40:41], v[64:65] op_sel_hi:[1,0,1]
	v_pk_fma_f32 v[16:17], v[16:17], v[40:41], v[66:67] op_sel_hi:[1,0,1]
	s_waitcnt vmcnt(2)
	v_lshlrev_b32_e32 v20, 16, v50
	v_and_b32_e32 v21, 0xffff0000, v50
	v_lshlrev_b32_e32 v22, 16, v51
	v_and_b32_e32 v23, 0xffff0000, v51
	v_pk_mul_f32 v[8:9], v[72:73], v[20:21]
	v_pk_mul_f32 v[10:11], v[74:75], v[22:23]
	v_pk_fma_f32 v[14:15], v[42:43], v[8:9], v[14:15] op_sel_hi:[0,1,1]
	v_pk_fma_f32 v[16:17], v[42:43], v[10:11], v[16:17] op_sel_hi:[0,1,1]
	s_waitcnt vmcnt(1)
	v_lshlrev_b32_e32 v20, 16, v52
	v_and_b32_e32 v21, 0xffff0000, v52
	v_lshlrev_b32_e32 v22, 16, v53
	v_and_b32_e32 v23, 0xffff0000, v53
	v_pk_mul_f32 v[8:9], v[76:77], v[20:21]
	v_pk_mul_f32 v[10:11], v[78:79], v[22:23]
	v_pk_fma_f32 v[14:15], v[44:45], v[8:9], v[14:15] op_sel_hi:[0,1,1]
	v_pk_fma_f32 v[16:17], v[44:45], v[10:11], v[16:17] op_sel_hi:[0,1,1]
	s_waitcnt vmcnt(0)
	v_lshlrev_b32_e32 v20, 16, v54
	v_and_b32_e32 v21, 0xffff0000, v54
	v_lshlrev_b32_e32 v22, 16, v55
	v_and_b32_e32 v23, 0xffff0000, v55
	v_pk_mul_f32 v[8:9], v[80:81], v[20:21]
	v_pk_mul_f32 v[10:11], v[82:83], v[22:23]
	v_pk_fma_f32 v[14:15], v[46:47], v[8:9], v[14:15] op_sel_hi:[0,1,1]
	v_pk_fma_f32 v[16:17], v[46:47], v[10:11], v[16:17] op_sel_hi:[0,1,1]
	v_cvt_pk_bf16_f32 v2, v14, v15
	v_cvt_pk_bf16_f32 v3, v16, v17
	global_store_dwordx2 v[0:1], v[2:3], off
	s_andn2_b64 exec, exec, s[12:13]
	s_cbranch_execnz .LBB0_1235
